# QK-norm (prep phase): gain loads of steps 1-5 hoisted above the first store into free registers, counted vmcnt waits (on top of v31)
# baseline (speedup 1.0000x reference)
; __device__ __forceinline__ float bflo(unsigned v) { return __uint_as_float(v << 16); }
; __device__ __forceinline__ float bfhi(unsigned v) { return __uint_as_float(v & 0xffff0000u); }
; __device__ __forceinline__ void phase_prep(PC p, int wv, int L, LAS unsigned char* lds) {
;     ...
;             const int tok = it * 32 + (tid >> 4), grp = tid & 15;
;             u16* q = z + (size_t)tok * NIN + grp * 64;
;             const float* gn = (grp < 8 ? p->a_qnorm : p->a_knorm) + L * 64;
;             const float sc = grp < 8 ? 0.125f * LOG2E : 1.0f;
;             u32x4 v[8]; float ss = 0.f;
; #pragma unroll
;             for (int i = 0; i < 8; ++i) {
;                 v[i] = ((const u32x4*)q)[i];
;                 const float a0 = bflo(v[i].x), a1 = bfhi(v[i].x), a2 = bflo(v[i].y), a3 = bfhi(v[i].y), a4 = bflo(v[i].z), a5 = bfhi(v[i].z), a6 = bflo(v[i].w), a7 = bfhi(v[i].w);
;                 ss += a0 * a0 + a1 * a1 + a2 * a2 + a3 * a3 + a4 * a4 + a5 * a5 + a6 * a6 + a7 * a7;
;             }
;             const float ri = rsqrtf(ss * (1.0f / 64.0f) + 1e-6f) * sc;
; #pragma unroll
;             for (int i = 0; i < 8; ++i) {
;                 const float* g = gn + i * 8;
;                 u32x4 o;
;                 o.x = pack2(bflo(v[i].x) * ri * g[0], bfhi(v[i].x) * ri * g[1]); o.y = pack2(bflo(v[i].y) * ri * g[2], bfhi(v[i].y) * ri * g[3]);
;                 o.z = pack2(bflo(v[i].z) * ri * g[4], bfhi(v[i].z) * ri * g[5]); o.w = pack2(bflo(v[i].w) * ri * g[6], bfhi(v[i].w) * ri * g[7]);
.LBB0_263:
	global_load_dwordx2 v[2:3], v[68:69], off
	v_lshl_add_u32 v0, s97, 5, v53
	v_mad_i64_i32 v[0:1], s[6:7], v0, s31, v[60:61]
	global_load_dwordx4 v[4:7], v[0:1], off offset:48
	global_load_dwordx4 v[8:11], v[0:1], off offset:32
	global_load_dwordx4 v[12:15], v[0:1], off offset:80
	global_load_dwordx4 v[16:19], v[0:1], off offset:64
	global_load_dwordx4 v[74:77], v[0:1], off offset:112
	global_load_dwordx4 v[78:81], v[0:1], off offset:96
	global_load_dwordx4 v[82:85], v[0:1], off
	global_load_dwordx4 v[86:89], v[0:1], off offset:16
	s_waitcnt vmcnt(8)
	global_load_dwordx4 v[90:93], v[2:3], off offset:16
	global_load_dwordx4 v[94:97], v[2:3], off
	s_waitcnt vmcnt(9)
	v_lshlrev_b32_e32 v47, 16, v4
	s_waitcnt vmcnt(8)
	v_lshlrev_b32_e32 v100, 16, v10
	v_and_b32_e32 v42, 0xffff0000, v10
	s_waitcnt vmcnt(7)
	v_lshlrev_b32_e32 v35, 16, v12
	v_and_b32_e32 v21, 0xffff0000, v12
	s_waitcnt vmcnt(4)
	v_lshlrev_b32_e32 v12, 16, v81
	v_and_b32_e32 v10, 0xffff0000, v81
	s_waitcnt vmcnt(3)
	v_and_b32_e32 v81, 0xffff0000, v82
	s_waitcnt vmcnt(2)
	v_and_b32_e32 v105, 0xffff0000, v86
	v_lshlrev_b32_e32 v46, 16, v8
	v_and_b32_e32 v38, 0xffff0000, v8
	v_lshlrev_b32_e32 v31, 16, v14
	v_and_b32_e32 v25, 0xffff0000, v14
	v_lshlrev_b32_e32 v14, 16, v80
	v_and_b32_e32 v8, 0xffff0000, v80
	v_lshlrev_b32_e32 v80, 16, v82
	v_lshlrev_b32_e32 v104, 16, v86
	v_mov_b32_e32 v122, v81
	v_mov_b32_e32 v123, v105
	v_and_b32_e32 v39, 0xffff0000, v4
	v_lshlrev_b32_e32 v99, 16, v5
	v_lshlrev_b32_e32 v98, 16, v9
	v_and_b32_e32 v41, 0xffff0000, v5
	v_and_b32_e32 v40, 0xffff0000, v9
	v_lshlrev_b32_e32 v103, 16, v7
	v_lshlrev_b32_e32 v102, 16, v11
	v_and_b32_e32 v45, 0xffff0000, v7
	v_and_b32_e32 v44, 0xffff0000, v11
	v_lshlrev_b32_e32 v33, 16, v13
	v_lshlrev_b32_e32 v32, 16, v17
	v_and_b32_e32 v23, 0xffff0000, v13
	v_and_b32_e32 v22, 0xffff0000, v17
	v_lshlrev_b32_e32 v30, 16, v18
	v_and_b32_e32 v24, 0xffff0000, v18
	v_lshlrev_b32_e32 v29, 16, v15
	v_lshlrev_b32_e32 v28, 16, v19
	v_and_b32_e32 v27, 0xffff0000, v15
	v_and_b32_e32 v26, 0xffff0000, v19
	v_lshlrev_b32_e32 v19, 16, v74
	v_lshlrev_b32_e32 v18, 16, v78
	v_and_b32_e32 v5, 0xffff0000, v74
	v_and_b32_e32 v4, 0xffff0000, v78
	v_lshlrev_b32_e32 v17, 16, v75
	v_and_b32_e32 v7, 0xffff0000, v75
	v_lshlrev_b32_e32 v15, 16, v76
	v_and_b32_e32 v9, 0xffff0000, v76
	v_lshlrev_b32_e32 v13, 16, v77
	v_and_b32_e32 v11, 0xffff0000, v77
	v_lshlrev_b32_e32 v74, 16, v85
	v_and_b32_e32 v75, 0xffff0000, v85
	v_lshlrev_b32_e32 v76, 16, v84
	v_and_b32_e32 v77, 0xffff0000, v84
	v_lshlrev_b32_e32 v78, 16, v83
	v_lshlrev_b32_e32 v84, 16, v88
	v_and_b32_e32 v85, 0xffff0000, v88
	v_lshlrev_b32_e32 v88, 16, v87
	v_mov_b32_e32 v120, v80
	v_mov_b32_e32 v121, v104
	v_pk_mul_f32 v[122:123], v[122:123], v[122:123]
	v_lshlrev_b32_e32 v101, 16, v6
	v_and_b32_e32 v43, 0xffff0000, v6
	v_lshlrev_b32_e32 v34, 16, v16
	v_and_b32_e32 v20, 0xffff0000, v16
	v_lshlrev_b32_e32 v16, 16, v79
	v_and_b32_e32 v6, 0xffff0000, v79
	v_and_b32_e32 v79, 0xffff0000, v83
	v_lshlrev_b32_e32 v82, 16, v89
	v_and_b32_e32 v83, 0xffff0000, v89
	v_and_b32_e32 v89, 0xffff0000, v87
	v_pk_mul_f32 v[36:37], v[38:39], v[38:39]
	v_mov_b32_e32 v116, v78
	v_mov_b32_e32 v117, v88
	v_pk_fma_f32 v[120:121], v[120:121], v[120:121], v[122:123]
	v_mov_b32_e32 v118, v79
	v_mov_b32_e32 v119, v89
	v_pk_fma_f32 v[36:37], v[46:47], v[46:47], v[36:37]
	v_pk_fma_f32 v[116:117], v[116:117], v[116:117], v[120:121]
	v_pk_mul_f32 v[86:87], v[20:21], v[20:21]
	v_mov_b32_e32 v112, v76
	v_mov_b32_e32 v113, v84
	v_pk_fma_f32 v[36:37], v[98:99], v[98:99], v[36:37]
	v_pk_fma_f32 v[116:117], v[118:119], v[118:119], v[116:117]
	v_mov_b32_e32 v114, v77
	v_mov_b32_e32 v115, v85
	v_pk_fma_f32 v[86:87], v[34:35], v[34:35], v[86:87]
	v_pk_fma_f32 v[36:37], v[40:41], v[40:41], v[36:37]
	v_pk_fma_f32 v[112:113], v[112:113], v[112:113], v[116:117]
	v_pk_mul_f32 v[106:107], v[4:5], v[4:5]
	v_mov_b32_e32 v108, v74
	v_mov_b32_e32 v109, v82
	v_pk_fma_f32 v[86:87], v[32:33], v[32:33], v[86:87]
	v_pk_fma_f32 v[36:37], v[100:101], v[100:101], v[36:37]
	v_pk_fma_f32 v[112:113], v[114:115], v[114:115], v[112:113]
	v_mov_b32_e32 v110, v75
	v_mov_b32_e32 v111, v83
	v_pk_fma_f32 v[106:107], v[18:19], v[18:19], v[106:107]
	v_pk_fma_f32 v[86:87], v[22:23], v[22:23], v[86:87]
	v_pk_fma_f32 v[36:37], v[42:43], v[42:43], v[36:37]
	v_pk_fma_f32 v[108:109], v[108:109], v[108:109], v[112:113]
	v_pk_fma_f32 v[106:107], v[16:17], v[16:17], v[106:107]
	v_pk_fma_f32 v[86:87], v[30:31], v[30:31], v[86:87]
	v_pk_fma_f32 v[36:37], v[102:103], v[102:103], v[36:37]
	v_pk_fma_f32 v[108:109], v[110:111], v[110:111], v[108:109]
	v_pk_fma_f32 v[106:107], v[6:7], v[6:7], v[106:107]
	v_pk_fma_f32 v[86:87], v[24:25], v[24:25], v[86:87]
	v_pk_fma_f32 v[36:37], v[44:45], v[44:45], v[36:37]
	v_add_f32_e32 v48, v108, v109
	v_pk_fma_f32 v[106:107], v[14:15], v[14:15], v[106:107]
	v_pk_fma_f32 v[86:87], v[28:29], v[28:29], v[86:87]
	v_add_f32_e32 v36, v48, v36
	v_pk_fma_f32 v[106:107], v[8:9], v[8:9], v[106:107]
	v_pk_fma_f32 v[86:87], v[26:27], v[26:27], v[86:87]
	v_add_f32_e32 v36, v36, v37
	v_pk_fma_f32 v[106:107], v[12:13], v[12:13], v[106:107]
	v_add_f32_e32 v36, v36, v86
	v_pk_fma_f32 v[106:107], v[10:11], v[10:11], v[106:107]
	v_add_f32_e32 v36, v36, v87
	v_add_f32_e32 v36, v36, v106
	v_add_f32_e32 v36, v36, v107
	v_fmamk_f32 v36, v36, 0x3c800000, v144
	v_mul_f32_e32 v37, 0x4b800000, v36
	v_cmp_gt_f32_e32 vcc, s37, v36
	s_nop 1
	v_cndmask_b32_e32 v36, v36, v37, vcc
	v_rsq_f32_e32 v36, v36
	s_nop 0
	v_mul_f32_e32 v37, 0x45800000, v36
	v_cndmask_b32_e32 v36, v36, v37, vcc
	v_mul_f32_e32 v36, v140, v36
	v_pk_mul_f32 v[80:81], v[36:37], v[80:81] op_sel_hi:[0,1]
	v_pk_mul_f32 v[78:79], v[36:37], v[78:79] op_sel_hi:[0,1]
	v_pk_mul_f32 v[76:77], v[36:37], v[76:77] op_sel_hi:[0,1]
	v_pk_mul_f32 v[74:75], v[36:37], v[74:75] op_sel_hi:[0,1]
	s_waitcnt vmcnt(0)
; __device__ __forceinline__ float bflo(unsigned v) { return __uint_as_float(v << 16); }
; __device__ __forceinline__ float bfhi(unsigned v) { return __uint_as_float(v & 0xffff0000u); }
; __device__ __forceinline__ void phase_prep(PC p, int wv, int L, LAS unsigned char* lds) {
;     ...
; #pragma unroll
;             for (int i = 0; i < 8; ++i) {
;                 const float* g = gn + i * 8;
;                 u32x4 o;
;                 o.x = pack2(bflo(v[i].x) * ri * g[0], bfhi(v[i].x) * ri * g[1]); o.y = pack2(bflo(v[i].y) * ri * g[2], bfhi(v[i].y) * ri * g[3]);
;                 o.z = pack2(bflo(v[i].z) * ri * g[4], bfhi(v[i].z) * ri * g[5]); o.w = pack2(bflo(v[i].w) * ri * g[6], bfhi(v[i].w) * ri * g[7]);
;                 ((u32x4*)q)[i] = o;
;             }
	v_pk_mul_f32 v[80:81], v[94:95], v[80:81]
	v_pk_mul_f32 v[78:79], v[96:97], v[78:79]
	v_pk_mul_f32 v[76:77], v[90:91], v[76:77]
	v_pk_mul_f32 v[86:87], v[92:93], v[74:75]
	v_cvt_pk_bf16_f32 v74, v80, v81
	v_cvt_pk_bf16_f32 v75, v78, v79
	v_cvt_pk_bf16_f32 v76, v76, v77
	v_cvt_pk_bf16_f32 v77, v86, v87
	global_load_dwordx4 v[202:205], v[2:3], off offset:32
	global_load_dwordx4 v[206:209], v[2:3], off offset:48
	global_load_dwordx4 v[210:213], v[2:3], off offset:64
	global_load_dwordx4 v[214:217], v[2:3], off offset:80
	global_load_dwordx4 v[218:221], v[2:3], off offset:96
	global_load_dwordx4 v[222:225], v[2:3], off offset:112
	global_load_dwordx4 v[226:229], v[2:3], off offset:128
	global_load_dwordx4 v[230:233], v[2:3], off offset:144
	global_load_dwordx4 v[234:237], v[2:3], off offset:160
	global_load_dwordx4 v[238:241], v[2:3], off offset:176
	global_store_dwordx4 v[0:1], v[74:77], off
	v_pk_mul_f32 v[86:87], v[36:37], v[104:105] op_sel_hi:[0,1]
	v_pk_mul_f32 v[88:89], v[36:37], v[88:89] op_sel_hi:[0,1]
	v_pk_mul_f32 v[84:85], v[36:37], v[84:85] op_sel_hi:[0,1]
	v_pk_mul_f32 v[82:83], v[36:37], v[82:83] op_sel_hi:[0,1]
	s_waitcnt vmcnt(10)
	v_pk_mul_f32 v[74:75], v[202:203], v[86:87]
	v_pk_mul_f32 v[76:77], v[204:205], v[88:89]
	s_waitcnt vmcnt(9)
	v_pk_mul_f32 v[78:79], v[206:207], v[84:85]
	v_pk_mul_f32 v[80:81], v[208:209], v[82:83]
	v_cvt_pk_bf16_f32 v74, v74, v75
	v_cvt_pk_bf16_f32 v75, v76, v77
	v_cvt_pk_bf16_f32 v76, v78, v79
	v_cvt_pk_bf16_f32 v77, v80, v81
	global_store_dwordx4 v[0:1], v[74:77], off offset:16
	v_mov_b32_e32 v82, v46
	v_mov_b32_e32 v83, v38
	v_mov_b32_e32 v84, v98
	v_mov_b32_e32 v85, v40
	v_mov_b32_e32 v86, v100
	v_mov_b32_e32 v87, v42
	v_mov_b32_e32 v88, v102
	v_mov_b32_e32 v89, v44
	v_pk_mul_f32 v[82:83], v[36:37], v[82:83] op_sel_hi:[0,1]
	v_pk_mul_f32 v[84:85], v[36:37], v[84:85] op_sel_hi:[0,1]
	v_pk_mul_f32 v[86:87], v[36:37], v[86:87] op_sel_hi:[0,1]
	v_pk_mul_f32 v[88:89], v[36:37], v[88:89] op_sel_hi:[0,1]
	v_mov_b32_e32 v38, v47
	v_mov_b32_e32 v40, v99
	v_mov_b32_e32 v42, v101
	v_mov_b32_e32 v44, v103
	v_pk_mul_f32 v[38:39], v[36:37], v[38:39] op_sel_hi:[0,1]
	v_pk_mul_f32 v[40:41], v[36:37], v[40:41] op_sel_hi:[0,1]
	v_pk_mul_f32 v[42:43], v[36:37], v[42:43] op_sel_hi:[0,1]
	v_pk_mul_f32 v[44:45], v[36:37], v[44:45] op_sel_hi:[0,1]
	v_mov_b32_e32 v46, v34
	v_mov_b32_e32 v47, v20
	v_pk_mul_f32 v[46:47], v[36:37], v[46:47] op_sel_hi:[0,1]
	v_mov_b32_e32 v20, v35
	v_pk_mul_f32 v[20:21], v[36:37], v[20:21] op_sel_hi:[0,1]
	v_mov_b32_e32 v34, v12
	v_mov_b32_e32 v35, v10
	v_pk_mul_f32 v[34:35], v[36:37], v[34:35] op_sel_hi:[0,1]
	v_mov_b32_e32 v10, v13
	s_waitcnt vmcnt(9)
	v_pk_mul_f32 v[74:75], v[210:211], v[82:83]
	v_pk_mul_f32 v[76:77], v[212:213], v[84:85]
	s_waitcnt vmcnt(8)
	v_pk_mul_f32 v[78:79], v[86:87], v[214:215]
	v_pk_mul_f32 v[80:81], v[88:89], v[216:217]
	v_cvt_pk_bf16_f32 v74, v74, v75
	v_cvt_pk_bf16_f32 v75, v76, v77
	v_cvt_pk_bf16_f32 v76, v78, v79
	v_cvt_pk_bf16_f32 v77, v80, v81
	global_store_dwordx4 v[0:1], v[74:77], off offset:32
	s_waitcnt vmcnt(8)
	v_pk_mul_f32 v[38:39], v[38:39], v[218:219]
	v_pk_mul_f32 v[40:41], v[40:41], v[220:221]
	s_waitcnt vmcnt(7)
	v_pk_mul_f32 v[42:43], v[42:43], v[222:223]
	v_pk_mul_f32 v[44:45], v[44:45], v[224:225]
	v_cvt_pk_bf16_f32 v38, v38, v39
	v_cvt_pk_bf16_f32 v39, v40, v41
	v_cvt_pk_bf16_f32 v40, v42, v43
	v_cvt_pk_bf16_f32 v41, v44, v45
	global_store_dwordx4 v[0:1], v[38:41], off offset:48
	v_mov_b32_e32 v74, v32
	v_mov_b32_e32 v75, v22
	v_mov_b32_e32 v76, v30
	v_mov_b32_e32 v77, v24
	v_mov_b32_e32 v78, v28
	v_mov_b32_e32 v79, v26
	v_pk_mul_f32 v[74:75], v[36:37], v[74:75] op_sel_hi:[0,1]
	v_pk_mul_f32 v[76:77], v[36:37], v[76:77] op_sel_hi:[0,1]
	v_pk_mul_f32 v[78:79], v[36:37], v[78:79] op_sel_hi:[0,1]
	v_mov_b32_e32 v22, v33
	v_mov_b32_e32 v24, v31
	v_mov_b32_e32 v26, v29
	v_pk_mul_f32 v[22:23], v[36:37], v[22:23] op_sel_hi:[0,1]
	v_pk_mul_f32 v[24:25], v[36:37], v[24:25] op_sel_hi:[0,1]
	v_pk_mul_f32 v[26:27], v[36:37], v[26:27] op_sel_hi:[0,1]
	v_mov_b32_e32 v28, v18
	v_mov_b32_e32 v29, v4
	v_mov_b32_e32 v30, v16
	v_mov_b32_e32 v31, v6
	v_mov_b32_e32 v32, v14
	v_mov_b32_e32 v33, v8
	v_pk_mul_f32 v[28:29], v[36:37], v[28:29] op_sel_hi:[0,1]
	v_pk_mul_f32 v[30:31], v[36:37], v[30:31] op_sel_hi:[0,1]
	v_pk_mul_f32 v[32:33], v[36:37], v[32:33] op_sel_hi:[0,1]
	v_mov_b32_e32 v4, v19
	v_mov_b32_e32 v6, v17
	v_mov_b32_e32 v8, v15
	s_waitcnt vmcnt(7)
	v_pk_mul_f32 v[38:39], v[46:47], v[226:227]
	v_pk_mul_f32 v[40:41], v[74:75], v[228:229]
	s_waitcnt vmcnt(6)
	v_pk_mul_f32 v[42:43], v[76:77], v[230:231]
	v_pk_mul_f32 v[44:45], v[78:79], v[232:233]
	v_cvt_pk_bf16_f32 v38, v38, v39
	v_cvt_pk_bf16_f32 v39, v40, v41
	v_cvt_pk_bf16_f32 v40, v42, v43
	v_cvt_pk_bf16_f32 v41, v44, v45
	global_store_dwordx4 v[0:1], v[38:41], off offset:64
	s_waitcnt vmcnt(6)
	v_pk_mul_f32 v[20:21], v[20:21], v[234:235]
	v_pk_mul_f32 v[22:23], v[22:23], v[236:237]
	s_waitcnt vmcnt(5)
	v_pk_mul_f32 v[24:25], v[24:25], v[238:239]
	v_pk_mul_f32 v[26:27], v[26:27], v[240:241]
	v_cvt_pk_bf16_f32 v20, v20, v21
	v_cvt_pk_bf16_f32 v21, v22, v23
	v_cvt_pk_bf16_f32 v22, v24, v25
	v_cvt_pk_bf16_f32 v23, v26, v27
	global_store_dwordx4 v[0:1], v[20:23], off offset:80
	global_load_dwordx4 v[20:23], v[2:3], off offset:192
	s_nop 0
	global_load_dwordx4 v[24:27], v[2:3], off offset:208
	s_waitcnt vmcnt(1)
	v_pk_mul_f32 v[20:21], v[28:29], v[20:21]
	v_pk_mul_f32 v[22:23], v[30:31], v[22:23]
	s_waitcnt vmcnt(0)
	v_pk_mul_f32 v[24:25], v[32:33], v[24:25]
	v_pk_mul_f32 v[26:27], v[34:35], v[26:27]
	v_cvt_pk_bf16_f32 v20, v20, v21
	v_cvt_pk_bf16_f32 v21, v22, v23
	v_cvt_pk_bf16_f32 v22, v24, v25
	v_cvt_pk_bf16_f32 v23, v26, v27
	global_store_dwordx4 v[0:1], v[20:23], off offset:96
	global_load_dwordx4 v[20:23], v[2:3], off offset:224
	s_nop 0
	global_load_dwordx4 v[24:27], v[2:3], off offset:240
	v_pk_mul_f32 v[2:3], v[36:37], v[4:5] op_sel_hi:[0,1]
	v_pk_mul_f32 v[4:5], v[36:37], v[6:7] op_sel_hi:[0,1]
	v_pk_mul_f32 v[6:7], v[36:37], v[8:9] op_sel_hi:[0,1]
	v_pk_mul_f32 v[8:9], v[36:37], v[10:11] op_sel_hi:[0,1]
	s_waitcnt vmcnt(1)
	v_pk_mul_f32 v[2:3], v[2:3], v[20:21]
	v_pk_mul_f32 v[4:5], v[4:5], v[22:23]
	s_waitcnt vmcnt(0)
	v_pk_mul_f32 v[6:7], v[6:7], v[24:25]
	v_pk_mul_f32 v[8:9], v[8:9], v[26:27]
	v_cvt_pk_bf16_f32 v2, v2, v3
	v_cvt_pk_bf16_f32 v3, v4, v5
	v_cvt_pk_bf16_f32 v4, v6, v7
	v_cvt_pk_bf16_f32 v5, v8, v9
	global_store_dwordx4 v[0:1], v[2:5], off offset:112
	s_branch .LBB0_108

; __device__ __forceinline__ float bflo(unsigned v) { return __uint_as_float(v << 16); }
; __device__ __forceinline__ float bfhi(unsigned v) { return __uint_as_float(v & 0xffff0000u); }
; __device__ __forceinline__ void phase_prep(PC p, int wv, int L, LAS unsigned char* lds) {
;     ...
;             const int tok = it * 32 + (tid >> 4), grp = tid & 15;
;             u16* q = z + (size_t)tok * NIN + grp * 64;
;             const float* gn = (grp < 8 ? p->a_qnorm : p->a_knorm) + L * 64;
;             const float sc = grp < 8 ? 0.125f * LOG2E : 1.0f;
;             u32x4 v[8]; float ss = 0.f;
; #pragma unroll
;             for (int i = 0; i < 8; ++i) {
;                 v[i] = ((const u32x4*)q)[i];
;                 const float a0 = bflo(v[i].x), a1 = bfhi(v[i].x), a2 = bflo(v[i].y), a3 = bfhi(v[i].y), a4 = bflo(v[i].z), a5 = bfhi(v[i].z), a6 = bflo(v[i].w), a7 = bfhi(v[i].w);
;                 ss += a0 * a0 + a1 * a1 + a2 * a2 + a3 * a3 + a4 * a4 + a5 * a5 + a6 * a6 + a7 * a7;
;             }
;             const float ri = rsqrtf(ss * (1.0f / 64.0f) + 1e-6f) * sc;
; #pragma unroll
;             for (int i = 0; i < 8; ++i) {
;                 const float* g = gn + i * 8;
;                 u32x4 o;
;                 o.x = pack2(bflo(v[i].x) * ri * g[0], bfhi(v[i].x) * ri * g[1]); o.y = pack2(bflo(v[i].y) * ri * g[2], bfhi(v[i].y) * ri * g[3]);
;                 o.z = pack2(bflo(v[i].z) * ri * g[4], bfhi(v[i].z) * ri * g[5]); o.w = pack2(bflo(v[i].w) * ri * g[6], bfhi(v[i].w) * ri * g[7]);
.LBB0_938:
	global_load_dwordx2 v[2:3], v[66:67], off
	v_lshl_add_u32 v0, s78, 5, v51
	v_mad_i64_i32 v[0:1], s[16:17], v0, s35, v[58:59]
	global_load_dwordx4 v[4:7], v[0:1], off offset:48
	global_load_dwordx4 v[8:11], v[0:1], off offset:32
	global_load_dwordx4 v[12:15], v[0:1], off offset:80
	global_load_dwordx4 v[16:19], v[0:1], off offset:64
	global_load_dwordx4 v[72:75], v[0:1], off offset:112
	global_load_dwordx4 v[76:79], v[0:1], off offset:96
	global_load_dwordx4 v[80:83], v[0:1], off
	global_load_dwordx4 v[84:87], v[0:1], off offset:16
	s_waitcnt vmcnt(8)
	global_load_dwordx4 v[88:91], v[2:3], off offset:272
	global_load_dwordx4 v[92:95], v[2:3], off offset:256
	s_waitcnt vmcnt(9)
	v_lshlrev_b32_e32 v47, 16, v4
	s_waitcnt vmcnt(8)
	v_lshlrev_b32_e32 v98, 16, v10
	v_and_b32_e32 v42, 0xffff0000, v10
	s_waitcnt vmcnt(7)
	v_lshlrev_b32_e32 v35, 16, v12
	v_and_b32_e32 v21, 0xffff0000, v12
	s_waitcnt vmcnt(4)
	v_lshlrev_b32_e32 v12, 16, v79
	v_and_b32_e32 v10, 0xffff0000, v79
	s_waitcnt vmcnt(3)
	v_and_b32_e32 v79, 0xffff0000, v80
	s_waitcnt vmcnt(2)
	v_and_b32_e32 v103, 0xffff0000, v84
	v_lshlrev_b32_e32 v46, 16, v8
	v_and_b32_e32 v38, 0xffff0000, v8
	v_lshlrev_b32_e32 v31, 16, v14
	v_and_b32_e32 v25, 0xffff0000, v14
	v_lshlrev_b32_e32 v14, 16, v78
	v_and_b32_e32 v8, 0xffff0000, v78
	v_lshlrev_b32_e32 v78, 16, v80
	v_lshlrev_b32_e32 v102, 16, v84
	v_mov_b32_e32 v120, v79
	v_mov_b32_e32 v121, v103
	v_and_b32_e32 v39, 0xffff0000, v4
	v_lshlrev_b32_e32 v97, 16, v5
	v_lshlrev_b32_e32 v96, 16, v9
	v_and_b32_e32 v41, 0xffff0000, v5
	v_and_b32_e32 v40, 0xffff0000, v9
	v_lshlrev_b32_e32 v101, 16, v7
	v_lshlrev_b32_e32 v100, 16, v11
	v_and_b32_e32 v45, 0xffff0000, v7
	v_and_b32_e32 v44, 0xffff0000, v11
	v_lshlrev_b32_e32 v33, 16, v13
	v_lshlrev_b32_e32 v32, 16, v17
	v_and_b32_e32 v23, 0xffff0000, v13
	v_and_b32_e32 v22, 0xffff0000, v17
	v_lshlrev_b32_e32 v30, 16, v18
	v_and_b32_e32 v24, 0xffff0000, v18
	v_lshlrev_b32_e32 v29, 16, v15
	v_lshlrev_b32_e32 v28, 16, v19
	v_and_b32_e32 v27, 0xffff0000, v15
	v_and_b32_e32 v26, 0xffff0000, v19
	v_lshlrev_b32_e32 v19, 16, v72
	v_lshlrev_b32_e32 v18, 16, v76
	v_and_b32_e32 v5, 0xffff0000, v72
	v_and_b32_e32 v4, 0xffff0000, v76
	v_lshlrev_b32_e32 v17, 16, v73
	v_and_b32_e32 v7, 0xffff0000, v73
	v_lshlrev_b32_e32 v15, 16, v74
	v_and_b32_e32 v9, 0xffff0000, v74
	v_lshlrev_b32_e32 v13, 16, v75
	v_and_b32_e32 v11, 0xffff0000, v75
	v_lshlrev_b32_e32 v72, 16, v83
	v_and_b32_e32 v73, 0xffff0000, v83
	v_lshlrev_b32_e32 v74, 16, v82
	v_and_b32_e32 v75, 0xffff0000, v82
	v_lshlrev_b32_e32 v76, 16, v81
	v_lshlrev_b32_e32 v82, 16, v86
	v_and_b32_e32 v83, 0xffff0000, v86
	v_lshlrev_b32_e32 v86, 16, v85
	v_mov_b32_e32 v118, v78
	v_mov_b32_e32 v119, v102
	v_pk_mul_f32 v[120:121], v[120:121], v[120:121]
	v_lshlrev_b32_e32 v99, 16, v6
	v_and_b32_e32 v43, 0xffff0000, v6
	v_lshlrev_b32_e32 v34, 16, v16
	v_and_b32_e32 v20, 0xffff0000, v16
	v_lshlrev_b32_e32 v16, 16, v77
	v_and_b32_e32 v6, 0xffff0000, v77
	v_and_b32_e32 v77, 0xffff0000, v81
	v_lshlrev_b32_e32 v80, 16, v87
	v_and_b32_e32 v81, 0xffff0000, v87
	v_and_b32_e32 v87, 0xffff0000, v85
	v_pk_mul_f32 v[36:37], v[38:39], v[38:39]
	v_mov_b32_e32 v114, v76
	v_mov_b32_e32 v115, v86
	v_pk_fma_f32 v[118:119], v[118:119], v[118:119], v[120:121]
	v_mov_b32_e32 v116, v77
	v_mov_b32_e32 v117, v87
	v_pk_fma_f32 v[36:37], v[46:47], v[46:47], v[36:37]
	v_pk_fma_f32 v[114:115], v[114:115], v[114:115], v[118:119]
	v_pk_mul_f32 v[84:85], v[20:21], v[20:21]
	v_mov_b32_e32 v110, v74
	v_mov_b32_e32 v111, v82
	v_pk_fma_f32 v[36:37], v[96:97], v[96:97], v[36:37]
	v_pk_fma_f32 v[114:115], v[116:117], v[116:117], v[114:115]
	v_mov_b32_e32 v112, v75
	v_mov_b32_e32 v113, v83
	v_pk_fma_f32 v[84:85], v[34:35], v[34:35], v[84:85]
	v_pk_fma_f32 v[36:37], v[40:41], v[40:41], v[36:37]
	v_pk_fma_f32 v[110:111], v[110:111], v[110:111], v[114:115]
	v_pk_mul_f32 v[104:105], v[4:5], v[4:5]
	v_mov_b32_e32 v106, v72
	v_mov_b32_e32 v107, v80
	v_pk_fma_f32 v[84:85], v[32:33], v[32:33], v[84:85]
	v_pk_fma_f32 v[36:37], v[98:99], v[98:99], v[36:37]
	v_pk_fma_f32 v[110:111], v[112:113], v[112:113], v[110:111]
	v_mov_b32_e32 v108, v73
	v_mov_b32_e32 v109, v81
	v_pk_fma_f32 v[104:105], v[18:19], v[18:19], v[104:105]
	v_pk_fma_f32 v[84:85], v[22:23], v[22:23], v[84:85]
	v_pk_fma_f32 v[36:37], v[42:43], v[42:43], v[36:37]
	v_pk_fma_f32 v[106:107], v[106:107], v[106:107], v[110:111]
	v_pk_fma_f32 v[104:105], v[16:17], v[16:17], v[104:105]
	v_pk_fma_f32 v[84:85], v[30:31], v[30:31], v[84:85]
	v_pk_fma_f32 v[36:37], v[100:101], v[100:101], v[36:37]
	v_pk_fma_f32 v[106:107], v[108:109], v[108:109], v[106:107]
	v_pk_fma_f32 v[104:105], v[6:7], v[6:7], v[104:105]
	v_pk_fma_f32 v[84:85], v[24:25], v[24:25], v[84:85]
	v_pk_fma_f32 v[36:37], v[44:45], v[44:45], v[36:37]
	v_add_f32_e32 v48, v106, v107
	v_pk_fma_f32 v[104:105], v[14:15], v[14:15], v[104:105]
	v_pk_fma_f32 v[84:85], v[28:29], v[28:29], v[84:85]
	v_add_f32_e32 v36, v48, v36
	v_pk_fma_f32 v[104:105], v[8:9], v[8:9], v[104:105]
	v_pk_fma_f32 v[84:85], v[26:27], v[26:27], v[84:85]
	v_add_f32_e32 v36, v36, v37
	v_pk_fma_f32 v[104:105], v[12:13], v[12:13], v[104:105]
	v_add_f32_e32 v36, v36, v84
	v_pk_fma_f32 v[104:105], v[10:11], v[10:11], v[104:105]
	v_add_f32_e32 v36, v36, v85
	v_add_f32_e32 v36, v36, v104
	v_add_f32_e32 v36, v36, v105
	v_fmamk_f32 v36, v36, 0x3c800000, v143
	v_mul_f32_e32 v37, 0x4b800000, v36
	v_cmp_gt_f32_e32 vcc, s37, v36
	s_nop 1
	v_cndmask_b32_e32 v36, v36, v37, vcc
	v_rsq_f32_e32 v36, v36
	s_nop 0
	v_mul_f32_e32 v37, 0x45800000, v36
	v_cndmask_b32_e32 v36, v36, v37, vcc
	v_mul_f32_e32 v36, v139, v36
	v_pk_mul_f32 v[78:79], v[36:37], v[78:79] op_sel_hi:[0,1]
	v_pk_mul_f32 v[76:77], v[36:37], v[76:77] op_sel_hi:[0,1]
	v_pk_mul_f32 v[74:75], v[36:37], v[74:75] op_sel_hi:[0,1]
	v_pk_mul_f32 v[72:73], v[36:37], v[72:73] op_sel_hi:[0,1]
	s_waitcnt vmcnt(0)
; __device__ __forceinline__ float bflo(unsigned v) { return __uint_as_float(v << 16); }
; __device__ __forceinline__ float bfhi(unsigned v) { return __uint_as_float(v & 0xffff0000u); }
; __device__ __forceinline__ void phase_prep(PC p, int wv, int L, LAS unsigned char* lds) {
;     ...
; #pragma unroll
;             for (int i = 0; i < 8; ++i) {
;                 const float* g = gn + i * 8;
;                 u32x4 o;
;                 o.x = pack2(bflo(v[i].x) * ri * g[0], bfhi(v[i].x) * ri * g[1]); o.y = pack2(bflo(v[i].y) * ri * g[2], bfhi(v[i].y) * ri * g[3]);
;                 o.z = pack2(bflo(v[i].z) * ri * g[4], bfhi(v[i].z) * ri * g[5]); o.w = pack2(bflo(v[i].w) * ri * g[6], bfhi(v[i].w) * ri * g[7]);
;                 ((u32x4*)q)[i] = o;
;             }
	v_pk_mul_f32 v[78:79], v[92:93], v[78:79]
	v_pk_mul_f32 v[76:77], v[94:95], v[76:77]
	v_pk_mul_f32 v[74:75], v[88:89], v[74:75]
	v_pk_mul_f32 v[84:85], v[90:91], v[72:73]
	v_cvt_pk_bf16_f32 v72, v78, v79
	v_cvt_pk_bf16_f32 v73, v76, v77
	v_cvt_pk_bf16_f32 v74, v74, v75
	v_cvt_pk_bf16_f32 v75, v84, v85
	global_load_dwordx4 v[202:205], v[2:3], off offset:288
	global_load_dwordx4 v[206:209], v[2:3], off offset:304
	global_load_dwordx4 v[210:213], v[2:3], off offset:320
	global_load_dwordx4 v[214:217], v[2:3], off offset:336
	global_load_dwordx4 v[218:221], v[2:3], off offset:352
	global_load_dwordx4 v[222:225], v[2:3], off offset:368
	global_load_dwordx4 v[226:229], v[2:3], off offset:384
	global_load_dwordx4 v[230:233], v[2:3], off offset:400
	global_load_dwordx4 v[234:237], v[2:3], off offset:416
	global_load_dwordx4 v[238:241], v[2:3], off offset:432
	global_store_dwordx4 v[0:1], v[72:75], off
	v_pk_mul_f32 v[84:85], v[36:37], v[102:103] op_sel_hi:[0,1]
	v_pk_mul_f32 v[86:87], v[36:37], v[86:87] op_sel_hi:[0,1]
	v_pk_mul_f32 v[82:83], v[36:37], v[82:83] op_sel_hi:[0,1]
	v_pk_mul_f32 v[80:81], v[36:37], v[80:81] op_sel_hi:[0,1]
	s_waitcnt vmcnt(10)
	v_pk_mul_f32 v[72:73], v[202:203], v[84:85]
	v_pk_mul_f32 v[74:75], v[204:205], v[86:87]
	s_waitcnt vmcnt(9)
	v_pk_mul_f32 v[76:77], v[206:207], v[82:83]
	v_pk_mul_f32 v[78:79], v[208:209], v[80:81]
	v_cvt_pk_bf16_f32 v72, v72, v73
	v_cvt_pk_bf16_f32 v73, v74, v75
	v_cvt_pk_bf16_f32 v74, v76, v77
	v_cvt_pk_bf16_f32 v75, v78, v79
	global_store_dwordx4 v[0:1], v[72:75], off offset:16
	v_mov_b32_e32 v80, v46
	v_mov_b32_e32 v81, v38
	v_mov_b32_e32 v82, v96
	v_mov_b32_e32 v83, v40
	v_mov_b32_e32 v84, v98
	v_mov_b32_e32 v85, v42
	v_mov_b32_e32 v86, v100
	v_mov_b32_e32 v87, v44
	v_pk_mul_f32 v[80:81], v[36:37], v[80:81] op_sel_hi:[0,1]
	v_pk_mul_f32 v[82:83], v[36:37], v[82:83] op_sel_hi:[0,1]
	v_pk_mul_f32 v[84:85], v[36:37], v[84:85] op_sel_hi:[0,1]
	v_pk_mul_f32 v[86:87], v[36:37], v[86:87] op_sel_hi:[0,1]
	v_mov_b32_e32 v38, v47
	v_mov_b32_e32 v40, v97
	v_mov_b32_e32 v42, v99
	v_mov_b32_e32 v44, v101
	v_pk_mul_f32 v[38:39], v[36:37], v[38:39] op_sel_hi:[0,1]
	v_pk_mul_f32 v[40:41], v[36:37], v[40:41] op_sel_hi:[0,1]
	v_pk_mul_f32 v[42:43], v[36:37], v[42:43] op_sel_hi:[0,1]
	v_pk_mul_f32 v[44:45], v[36:37], v[44:45] op_sel_hi:[0,1]
	v_mov_b32_e32 v46, v34
	v_mov_b32_e32 v47, v20
	v_pk_mul_f32 v[46:47], v[36:37], v[46:47] op_sel_hi:[0,1]
	v_mov_b32_e32 v20, v35
	v_pk_mul_f32 v[20:21], v[36:37], v[20:21] op_sel_hi:[0,1]
	v_mov_b32_e32 v34, v12
	v_mov_b32_e32 v35, v10
	v_pk_mul_f32 v[34:35], v[36:37], v[34:35] op_sel_hi:[0,1]
	v_mov_b32_e32 v10, v13
	s_waitcnt vmcnt(9)
	v_pk_mul_f32 v[72:73], v[210:211], v[80:81]
	v_pk_mul_f32 v[74:75], v[212:213], v[82:83]
	s_waitcnt vmcnt(8)
	v_pk_mul_f32 v[76:77], v[84:85], v[214:215]
	v_pk_mul_f32 v[78:79], v[86:87], v[216:217]
	v_cvt_pk_bf16_f32 v72, v72, v73
	v_cvt_pk_bf16_f32 v73, v74, v75
	v_cvt_pk_bf16_f32 v74, v76, v77
	v_cvt_pk_bf16_f32 v75, v78, v79
	global_store_dwordx4 v[0:1], v[72:75], off offset:32
	s_waitcnt vmcnt(8)
	v_pk_mul_f32 v[38:39], v[38:39], v[218:219]
	v_pk_mul_f32 v[40:41], v[40:41], v[220:221]
	s_waitcnt vmcnt(7)
	v_pk_mul_f32 v[42:43], v[42:43], v[222:223]
	v_pk_mul_f32 v[44:45], v[44:45], v[224:225]
	v_cvt_pk_bf16_f32 v38, v38, v39
	v_cvt_pk_bf16_f32 v39, v40, v41
	v_cvt_pk_bf16_f32 v40, v42, v43
	v_cvt_pk_bf16_f32 v41, v44, v45
	global_store_dwordx4 v[0:1], v[38:41], off offset:48
	v_mov_b32_e32 v72, v32
	v_mov_b32_e32 v73, v22
	v_mov_b32_e32 v74, v30
	v_mov_b32_e32 v75, v24
	v_mov_b32_e32 v76, v28
	v_mov_b32_e32 v77, v26
	v_pk_mul_f32 v[72:73], v[36:37], v[72:73] op_sel_hi:[0,1]
	v_pk_mul_f32 v[74:75], v[36:37], v[74:75] op_sel_hi:[0,1]
	v_pk_mul_f32 v[76:77], v[36:37], v[76:77] op_sel_hi:[0,1]
	v_mov_b32_e32 v22, v33
	v_mov_b32_e32 v24, v31
	v_mov_b32_e32 v26, v29
	v_pk_mul_f32 v[22:23], v[36:37], v[22:23] op_sel_hi:[0,1]
	v_pk_mul_f32 v[24:25], v[36:37], v[24:25] op_sel_hi:[0,1]
	v_pk_mul_f32 v[26:27], v[36:37], v[26:27] op_sel_hi:[0,1]
	v_mov_b32_e32 v28, v18
	v_mov_b32_e32 v29, v4
	v_mov_b32_e32 v30, v16
	v_mov_b32_e32 v31, v6
	v_mov_b32_e32 v32, v14
	v_mov_b32_e32 v33, v8
	v_pk_mul_f32 v[28:29], v[36:37], v[28:29] op_sel_hi:[0,1]
	v_pk_mul_f32 v[30:31], v[36:37], v[30:31] op_sel_hi:[0,1]
	v_pk_mul_f32 v[32:33], v[36:37], v[32:33] op_sel_hi:[0,1]
	v_mov_b32_e32 v4, v19
	v_mov_b32_e32 v6, v17
	v_mov_b32_e32 v8, v15
	s_waitcnt vmcnt(7)
	v_pk_mul_f32 v[38:39], v[46:47], v[226:227]
	v_pk_mul_f32 v[40:41], v[72:73], v[228:229]
	s_waitcnt vmcnt(6)
	v_pk_mul_f32 v[42:43], v[74:75], v[230:231]
	v_pk_mul_f32 v[44:45], v[76:77], v[232:233]
	v_cvt_pk_bf16_f32 v38, v38, v39
	v_cvt_pk_bf16_f32 v39, v40, v41
	v_cvt_pk_bf16_f32 v40, v42, v43
	v_cvt_pk_bf16_f32 v41, v44, v45
	global_store_dwordx4 v[0:1], v[38:41], off offset:64
	s_waitcnt vmcnt(6)
	v_pk_mul_f32 v[20:21], v[20:21], v[234:235]
	v_pk_mul_f32 v[22:23], v[22:23], v[236:237]
	s_waitcnt vmcnt(5)
	v_pk_mul_f32 v[24:25], v[24:25], v[238:239]
	v_pk_mul_f32 v[26:27], v[26:27], v[240:241]
	v_cvt_pk_bf16_f32 v20, v20, v21
	v_cvt_pk_bf16_f32 v21, v22, v23
	v_cvt_pk_bf16_f32 v22, v24, v25
	v_cvt_pk_bf16_f32 v23, v26, v27
	global_store_dwordx4 v[0:1], v[20:23], off offset:80
	global_load_dwordx4 v[20:23], v[2:3], off offset:448
	s_nop 0
	global_load_dwordx4 v[24:27], v[2:3], off offset:464
	s_waitcnt vmcnt(1)
	v_pk_mul_f32 v[20:21], v[28:29], v[20:21]
	v_pk_mul_f32 v[22:23], v[30:31], v[22:23]
	s_waitcnt vmcnt(0)
	v_pk_mul_f32 v[24:25], v[32:33], v[24:25]
	v_pk_mul_f32 v[26:27], v[34:35], v[26:27]
	v_cvt_pk_bf16_f32 v20, v20, v21
	v_cvt_pk_bf16_f32 v21, v22, v23
	v_cvt_pk_bf16_f32 v22, v24, v25
	v_cvt_pk_bf16_f32 v23, v26, v27
	global_store_dwordx4 v[0:1], v[20:23], off offset:96
	global_load_dwordx4 v[20:23], v[2:3], off offset:480
	s_nop 0
	global_load_dwordx4 v[24:27], v[2:3], off offset:496
	v_pk_mul_f32 v[2:3], v[36:37], v[4:5] op_sel_hi:[0,1]
	v_pk_mul_f32 v[4:5], v[36:37], v[6:7] op_sel_hi:[0,1]
	v_pk_mul_f32 v[6:7], v[36:37], v[8:9] op_sel_hi:[0,1]
	v_pk_mul_f32 v[8:9], v[36:37], v[10:11] op_sel_hi:[0,1]
	s_waitcnt vmcnt(1)
	v_pk_mul_f32 v[2:3], v[2:3], v[20:21]
	v_pk_mul_f32 v[4:5], v[4:5], v[22:23]
	s_waitcnt vmcnt(0)
	v_pk_mul_f32 v[6:7], v[6:7], v[24:25]
	v_pk_mul_f32 v[8:9], v[8:9], v[26:27]
	v_cvt_pk_bf16_f32 v2, v2, v3
	v_cvt_pk_bf16_f32 v3, v4, v5
	v_cvt_pk_bf16_f32 v4, v6, v7
	v_cvt_pk_bf16_f32 v5, v8, v9
	global_store_dwordx4 v[0:1], v[2:5], off offset:112
	s_branch .LBB0_783
